# speedup vs baseline: 1.0034x; 1.0034x over previous
.LBB0_768:
	s_and_b64 vcc, exec, s[6:7]
	s_cbranch_vccz .LBB0_247
	s_cmp_gt_i32 s2, 29
	s_cselect_b64 s[24:25], -1, 0
	v_mov_b32_e32 v132, 0xbfb8aa3b
	v_mov_b32_e32 v133, 0xbfb8aa3b
	s_cmp_lt_i32 s2, 30
	s_cbranch_scc1 .LBB0_771
	v_pk_mul_f32 v[122:123], v[122:123], v[132:133]
	v_pk_mul_f32 v[124:125], v[124:125], v[132:133]
	v_pk_mul_f32 v[126:127], v[126:127], v[132:133]
	v_pk_mul_f32 v[128:129], v[128:129], v[132:133]
	v_exp_f32_e32 v122, v122
	v_exp_f32_e32 v123, v123
	v_exp_f32_e32 v124, v124
	v_exp_f32_e32 v125, v125
	v_exp_f32_e32 v126, v126
	v_exp_f32_e32 v127, v127
	v_exp_f32_e32 v128, v128
	v_exp_f32_e32 v129, v129
	v_pk_add_f32 v[122:123], v[122:123], 1.0 op_sel_hi:[1,0]
	v_pk_add_f32 v[124:125], v[124:125], 1.0 op_sel_hi:[1,0]
	v_pk_add_f32 v[126:127], v[126:127], 1.0 op_sel_hi:[1,0]
	v_pk_add_f32 v[128:129], v[128:129], 1.0 op_sel_hi:[1,0]
	v_rcp_f32_e32 v122, v122
	v_rcp_f32_e32 v123, v123
	v_rcp_f32_e32 v124, v124
	v_rcp_f32_e32 v125, v125
	v_rcp_f32_e32 v126, v126
	v_rcp_f32_e32 v127, v127
	v_rcp_f32_e32 v128, v128
	v_rcp_f32_e32 v129, v129
.LBB0_771:
	v_mov_b64_e32 v[130:131], s[34:35]
	v_mad_i64_i32 v[130:131], s[6:7], v198, s62, v[130:131]
	v_lshl_add_u64 v[130:131], s[94:95], 1, v[130:131]
	v_lshlrev_b32_e32 v0, 1, v230
	v_lshl_add_u64 v[130:131], v[130:131], 0, v[0:1]
	v_lshlrev_b32_e32 v0, 1, v231
	v_lshl_add_u64 v[130:131], v[130:131], 0, v[0:1]
	v_cvt_pk_bf16_f32 v126, v126, v127
	v_cvt_pk_bf16_f32 v127, v128, v129
	v_cvt_pk_bf16_f32 v128, v122, v123
	v_cvt_pk_bf16_f32 v129, v124, v125
	v_cndmask_b32_e64 v0, 0, 1, s[24:25]
	v_permlane16_swap_b32_e32 v126, v128
	v_permlane16_swap_b32_e32 v127, v129
	v_cmp_ne_u32_e64 s[6:7], 1, v0
	s_andn2_b64 vcc, exec, s[24:25]
	global_store_dwordx4 v[130:131], v[126:129], off
	s_cbranch_vccnz .LBB0_773
	v_pk_mul_f32 v[114:115], v[114:115], v[132:133]
	v_pk_mul_f32 v[116:117], v[116:117], v[132:133]
	v_pk_mul_f32 v[118:119], v[118:119], v[132:133]
	v_pk_mul_f32 v[120:121], v[120:121], v[132:133]
	v_exp_f32_e32 v114, v114
	v_exp_f32_e32 v115, v115
	v_exp_f32_e32 v116, v116
	v_exp_f32_e32 v117, v117
	v_exp_f32_e32 v118, v118
	v_exp_f32_e32 v119, v119
	v_exp_f32_e32 v120, v120
	v_exp_f32_e32 v121, v121
	v_pk_add_f32 v[114:115], v[114:115], 1.0 op_sel_hi:[1,0]
	v_pk_add_f32 v[116:117], v[116:117], 1.0 op_sel_hi:[1,0]
	v_pk_add_f32 v[118:119], v[118:119], 1.0 op_sel_hi:[1,0]
	v_pk_add_f32 v[120:121], v[120:121], 1.0 op_sel_hi:[1,0]
	v_rcp_f32_e32 v114, v114
	v_rcp_f32_e32 v115, v115
	v_rcp_f32_e32 v116, v116
	v_rcp_f32_e32 v117, v117
	v_rcp_f32_e32 v118, v118
	v_rcp_f32_e32 v119, v119
	v_rcp_f32_e32 v120, v120
	v_rcp_f32_e32 v121, v121
.LBB0_773:
	v_cvt_pk_bf16_f32 v118, v118, v119
	v_cvt_pk_bf16_f32 v119, v120, v121
	v_cvt_pk_bf16_f32 v120, v114, v115
	v_add_co_u32_e32 v114, vcc, 0x6c000, v130
	v_cvt_pk_bf16_f32 v121, v116, v117
	s_nop 0
	v_addc_co_u32_e32 v115, vcc, 0, v131, vcc
	v_permlane16_swap_b32_e32 v118, v120
	v_permlane16_swap_b32_e32 v119, v121
	s_and_b64 vcc, exec, s[6:7]
	global_store_dwordx4 v[114:115], v[118:121], off
	s_cbranch_vccnz .LBB0_775
	v_pk_mul_f32 v[106:107], v[106:107], v[132:133]
	v_pk_mul_f32 v[108:109], v[108:109], v[132:133]
	v_pk_mul_f32 v[110:111], v[110:111], v[132:133]
	v_pk_mul_f32 v[112:113], v[112:113], v[132:133]
	v_exp_f32_e32 v106, v106
	v_exp_f32_e32 v107, v107
	v_exp_f32_e32 v108, v108
	v_exp_f32_e32 v109, v109
	v_exp_f32_e32 v110, v110
	v_exp_f32_e32 v111, v111
	v_exp_f32_e32 v112, v112
	v_exp_f32_e32 v113, v113
	v_pk_add_f32 v[106:107], v[106:107], 1.0 op_sel_hi:[1,0]
	v_pk_add_f32 v[108:109], v[108:109], 1.0 op_sel_hi:[1,0]
	v_pk_add_f32 v[110:111], v[110:111], 1.0 op_sel_hi:[1,0]
	v_pk_add_f32 v[112:113], v[112:113], 1.0 op_sel_hi:[1,0]
	v_rcp_f32_e32 v106, v106
	v_rcp_f32_e32 v107, v107
	v_rcp_f32_e32 v108, v108
	v_rcp_f32_e32 v109, v109
	v_rcp_f32_e32 v110, v110
	v_rcp_f32_e32 v111, v111
	v_rcp_f32_e32 v112, v112
	v_rcp_f32_e32 v113, v113
.LBB0_775:
	v_cvt_pk_bf16_f32 v110, v110, v111
	v_cvt_pk_bf16_f32 v111, v112, v113
	v_cvt_pk_bf16_f32 v112, v106, v107
	v_add_co_u32_e32 v106, vcc, 0xd8000, v130
	v_cvt_pk_bf16_f32 v113, v108, v109
	s_nop 0
	v_addc_co_u32_e32 v107, vcc, 0, v131, vcc
	v_permlane16_swap_b32_e32 v110, v112
	v_permlane16_swap_b32_e32 v111, v113
	s_and_b64 vcc, exec, s[6:7]
	global_store_dwordx4 v[106:107], v[110:113], off
	s_cbranch_vccnz .LBB0_777
	v_pk_mul_f32 v[98:99], v[98:99], v[132:133]
	v_pk_mul_f32 v[100:101], v[100:101], v[132:133]
	v_pk_mul_f32 v[102:103], v[102:103], v[132:133]
	v_pk_mul_f32 v[104:105], v[104:105], v[132:133]
	v_exp_f32_e32 v98, v98
	v_exp_f32_e32 v99, v99
	v_exp_f32_e32 v100, v100
	v_exp_f32_e32 v101, v101
	v_exp_f32_e32 v102, v102
	v_exp_f32_e32 v103, v103
	v_exp_f32_e32 v104, v104
	v_exp_f32_e32 v105, v105
	v_pk_add_f32 v[98:99], v[98:99], 1.0 op_sel_hi:[1,0]
	v_pk_add_f32 v[100:101], v[100:101], 1.0 op_sel_hi:[1,0]
	v_pk_add_f32 v[102:103], v[102:103], 1.0 op_sel_hi:[1,0]
	v_pk_add_f32 v[104:105], v[104:105], 1.0 op_sel_hi:[1,0]
	v_rcp_f32_e32 v98, v98
	v_rcp_f32_e32 v99, v99
	v_rcp_f32_e32 v100, v100
	v_rcp_f32_e32 v101, v101
	v_rcp_f32_e32 v102, v102
	v_rcp_f32_e32 v103, v103
	v_rcp_f32_e32 v104, v104
	v_rcp_f32_e32 v105, v105
.LBB0_777:
	v_cvt_pk_bf16_f32 v102, v102, v103
	v_cvt_pk_bf16_f32 v103, v104, v105
	v_cvt_pk_bf16_f32 v104, v98, v99
	v_add_co_u32_e32 v98, vcc, 0x144000, v130
	v_cvt_pk_bf16_f32 v105, v100, v101
	s_nop 0
	v_addc_co_u32_e32 v99, vcc, 0, v131, vcc
	v_permlane16_swap_b32_e32 v102, v104
	v_permlane16_swap_b32_e32 v103, v105
	s_and_b64 vcc, exec, s[6:7]
	global_store_dwordx4 v[98:99], v[102:105], off
	s_cbranch_vccnz .LBB0_779
	v_pk_mul_f32 v[90:91], v[90:91], v[132:133]
	v_pk_mul_f32 v[92:93], v[92:93], v[132:133]
	v_pk_mul_f32 v[94:95], v[94:95], v[132:133]
	v_pk_mul_f32 v[96:97], v[96:97], v[132:133]
	v_exp_f32_e32 v90, v90
	v_exp_f32_e32 v91, v91
	v_exp_f32_e32 v92, v92
	v_exp_f32_e32 v93, v93
	v_exp_f32_e32 v94, v94
	v_exp_f32_e32 v95, v95
	v_exp_f32_e32 v96, v96
	v_exp_f32_e32 v97, v97
	v_pk_add_f32 v[90:91], v[90:91], 1.0 op_sel_hi:[1,0]
	v_pk_add_f32 v[92:93], v[92:93], 1.0 op_sel_hi:[1,0]
	v_pk_add_f32 v[94:95], v[94:95], 1.0 op_sel_hi:[1,0]
	v_pk_add_f32 v[96:97], v[96:97], 1.0 op_sel_hi:[1,0]
	v_rcp_f32_e32 v90, v90
	v_rcp_f32_e32 v91, v91
	v_rcp_f32_e32 v92, v92
	v_rcp_f32_e32 v93, v93
	v_rcp_f32_e32 v94, v94
	v_rcp_f32_e32 v95, v95
	v_rcp_f32_e32 v96, v96
	v_rcp_f32_e32 v97, v97
.LBB0_779:
	v_cvt_pk_bf16_f32 v94, v94, v95
	v_cvt_pk_bf16_f32 v95, v96, v97
	v_cvt_pk_bf16_f32 v96, v90, v91
	v_cvt_pk_bf16_f32 v97, v92, v93
	s_nop 0
	v_permlane16_swap_b32_e32 v94, v96
	v_permlane16_swap_b32_e32 v95, v97
	s_and_b64 vcc, exec, s[6:7]
	global_store_dwordx4 v[130:131], v[94:97], off offset:256
	s_cbranch_vccnz .LBB0_781
	v_pk_mul_f32 v[82:83], v[82:83], v[132:133]
	v_pk_mul_f32 v[84:85], v[84:85], v[132:133]
	v_pk_mul_f32 v[86:87], v[86:87], v[132:133]
	v_pk_mul_f32 v[88:89], v[88:89], v[132:133]
	v_exp_f32_e32 v82, v82
	v_exp_f32_e32 v83, v83
	v_exp_f32_e32 v84, v84
	v_exp_f32_e32 v85, v85
	v_exp_f32_e32 v86, v86
	v_exp_f32_e32 v87, v87
	v_exp_f32_e32 v88, v88
	v_exp_f32_e32 v89, v89
	v_pk_add_f32 v[82:83], v[82:83], 1.0 op_sel_hi:[1,0]
	v_pk_add_f32 v[84:85], v[84:85], 1.0 op_sel_hi:[1,0]
	v_pk_add_f32 v[86:87], v[86:87], 1.0 op_sel_hi:[1,0]
	v_pk_add_f32 v[88:89], v[88:89], 1.0 op_sel_hi:[1,0]
	v_rcp_f32_e32 v82, v82
	v_rcp_f32_e32 v83, v83
	v_rcp_f32_e32 v84, v84
	v_rcp_f32_e32 v85, v85
	v_rcp_f32_e32 v86, v86
	v_rcp_f32_e32 v87, v87
	v_rcp_f32_e32 v88, v88
	v_rcp_f32_e32 v89, v89
.LBB0_781:
	v_cvt_pk_bf16_f32 v86, v86, v87
	v_cvt_pk_bf16_f32 v87, v88, v89
	v_cvt_pk_bf16_f32 v88, v82, v83
	v_add_co_u32_e32 v82, vcc, 0x6c000, v130
	v_cvt_pk_bf16_f32 v89, v84, v85
	s_nop 0
	v_addc_co_u32_e32 v83, vcc, 0, v131, vcc
	v_permlane16_swap_b32_e32 v86, v88
	v_permlane16_swap_b32_e32 v87, v89
	s_and_b64 vcc, exec, s[6:7]
	global_store_dwordx4 v[82:83], v[86:89], off offset:256
	s_cbranch_vccnz .LBB0_783
	v_pk_mul_f32 v[74:75], v[74:75], v[132:133]
	v_pk_mul_f32 v[76:77], v[76:77], v[132:133]
	v_pk_mul_f32 v[78:79], v[78:79], v[132:133]
	v_pk_mul_f32 v[80:81], v[80:81], v[132:133]
	v_exp_f32_e32 v74, v74
	v_exp_f32_e32 v75, v75
	v_exp_f32_e32 v76, v76
	v_exp_f32_e32 v77, v77
	v_exp_f32_e32 v78, v78
	v_exp_f32_e32 v79, v79
	v_exp_f32_e32 v80, v80
	v_exp_f32_e32 v81, v81
	v_pk_add_f32 v[74:75], v[74:75], 1.0 op_sel_hi:[1,0]
	v_pk_add_f32 v[76:77], v[76:77], 1.0 op_sel_hi:[1,0]
	v_pk_add_f32 v[78:79], v[78:79], 1.0 op_sel_hi:[1,0]
	v_pk_add_f32 v[80:81], v[80:81], 1.0 op_sel_hi:[1,0]
	v_rcp_f32_e32 v74, v74
	v_rcp_f32_e32 v75, v75
	v_rcp_f32_e32 v76, v76
	v_rcp_f32_e32 v77, v77
	v_rcp_f32_e32 v78, v78
	v_rcp_f32_e32 v79, v79
	v_rcp_f32_e32 v80, v80
	v_rcp_f32_e32 v81, v81
.LBB0_783:
	v_cvt_pk_bf16_f32 v78, v78, v79
	v_cvt_pk_bf16_f32 v79, v80, v81
	v_cvt_pk_bf16_f32 v80, v74, v75
	v_add_co_u32_e32 v74, vcc, 0xd8000, v130
	v_cvt_pk_bf16_f32 v81, v76, v77
	s_nop 0
	v_addc_co_u32_e32 v75, vcc, 0, v131, vcc
	v_permlane16_swap_b32_e32 v78, v80
	v_permlane16_swap_b32_e32 v79, v81
	s_and_b64 vcc, exec, s[6:7]
	global_store_dwordx4 v[74:75], v[78:81], off offset:256
	s_cbranch_vccnz .LBB0_785
	v_pk_mul_f32 v[66:67], v[66:67], v[132:133]
	v_pk_mul_f32 v[68:69], v[68:69], v[132:133]
	v_pk_mul_f32 v[70:71], v[70:71], v[132:133]
	v_pk_mul_f32 v[72:73], v[72:73], v[132:133]
	v_exp_f32_e32 v66, v66
	v_exp_f32_e32 v67, v67
	v_exp_f32_e32 v68, v68
	v_exp_f32_e32 v69, v69
	v_exp_f32_e32 v70, v70
	v_exp_f32_e32 v71, v71
	v_exp_f32_e32 v72, v72
	v_exp_f32_e32 v73, v73
	v_pk_add_f32 v[66:67], v[66:67], 1.0 op_sel_hi:[1,0]
	v_pk_add_f32 v[68:69], v[68:69], 1.0 op_sel_hi:[1,0]
	v_pk_add_f32 v[70:71], v[70:71], 1.0 op_sel_hi:[1,0]
	v_pk_add_f32 v[72:73], v[72:73], 1.0 op_sel_hi:[1,0]
	v_rcp_f32_e32 v66, v66
	v_rcp_f32_e32 v67, v67
	v_rcp_f32_e32 v68, v68
	v_rcp_f32_e32 v69, v69
	v_rcp_f32_e32 v70, v70
	v_rcp_f32_e32 v71, v71
	v_rcp_f32_e32 v72, v72
	v_rcp_f32_e32 v73, v73
.LBB0_785:
	v_cvt_pk_bf16_f32 v70, v70, v71
	v_cvt_pk_bf16_f32 v71, v72, v73
	v_cvt_pk_bf16_f32 v72, v66, v67
	v_add_co_u32_e32 v66, vcc, 0x144000, v130
	v_cvt_pk_bf16_f32 v73, v68, v69
	s_nop 0
	v_addc_co_u32_e32 v67, vcc, 0, v131, vcc
	v_permlane16_swap_b32_e32 v70, v72
	v_permlane16_swap_b32_e32 v71, v73
	s_and_b64 vcc, exec, s[6:7]
	global_store_dwordx4 v[66:67], v[70:73], off offset:256
	s_cbranch_vccnz .LBB0_787
	v_pk_mul_f32 v[58:59], v[58:59], v[132:133]
	v_pk_mul_f32 v[60:61], v[60:61], v[132:133]
	v_pk_mul_f32 v[62:63], v[62:63], v[132:133]
	v_pk_mul_f32 v[64:65], v[64:65], v[132:133]
	v_exp_f32_e32 v58, v58
	v_exp_f32_e32 v59, v59
	v_exp_f32_e32 v60, v60
	v_exp_f32_e32 v61, v61
	v_exp_f32_e32 v62, v62
	v_exp_f32_e32 v63, v63
	v_exp_f32_e32 v64, v64
	v_exp_f32_e32 v65, v65
	v_pk_add_f32 v[58:59], v[58:59], 1.0 op_sel_hi:[1,0]
	v_pk_add_f32 v[60:61], v[60:61], 1.0 op_sel_hi:[1,0]
	v_pk_add_f32 v[62:63], v[62:63], 1.0 op_sel_hi:[1,0]
	v_pk_add_f32 v[64:65], v[64:65], 1.0 op_sel_hi:[1,0]
	v_rcp_f32_e32 v58, v58
	v_rcp_f32_e32 v59, v59
	v_rcp_f32_e32 v60, v60
	v_rcp_f32_e32 v61, v61
	v_rcp_f32_e32 v62, v62
	v_rcp_f32_e32 v63, v63
	v_rcp_f32_e32 v64, v64
	v_rcp_f32_e32 v65, v65
.LBB0_787:
	v_cvt_pk_bf16_f32 v62, v62, v63
	v_cvt_pk_bf16_f32 v63, v64, v65
	v_cvt_pk_bf16_f32 v64, v58, v59
	v_add_co_u32_e32 v58, vcc, 0x360000, v130
	v_cvt_pk_bf16_f32 v65, v60, v61
	s_nop 0
	v_addc_co_u32_e32 v59, vcc, 0, v131, vcc
	v_permlane16_swap_b32_e32 v62, v64
	v_permlane16_swap_b32_e32 v63, v65
	s_and_b64 vcc, exec, s[6:7]
	global_store_dwordx4 v[58:59], v[62:65], off
	s_cbranch_vccnz .LBB0_789
	v_pk_mul_f32 v[50:51], v[50:51], v[132:133]
	v_pk_mul_f32 v[52:53], v[52:53], v[132:133]
	v_pk_mul_f32 v[54:55], v[54:55], v[132:133]
	v_pk_mul_f32 v[56:57], v[56:57], v[132:133]
	v_exp_f32_e32 v50, v50
	v_exp_f32_e32 v51, v51
	v_exp_f32_e32 v52, v52
	v_exp_f32_e32 v53, v53
	v_exp_f32_e32 v54, v54
	v_exp_f32_e32 v55, v55
	v_exp_f32_e32 v56, v56
	v_exp_f32_e32 v57, v57
	v_pk_add_f32 v[50:51], v[50:51], 1.0 op_sel_hi:[1,0]
	v_pk_add_f32 v[52:53], v[52:53], 1.0 op_sel_hi:[1,0]
	v_pk_add_f32 v[54:55], v[54:55], 1.0 op_sel_hi:[1,0]
	v_pk_add_f32 v[56:57], v[56:57], 1.0 op_sel_hi:[1,0]
	v_rcp_f32_e32 v50, v50
	v_rcp_f32_e32 v51, v51
	v_rcp_f32_e32 v52, v52
	v_rcp_f32_e32 v53, v53
	v_rcp_f32_e32 v54, v54
	v_rcp_f32_e32 v55, v55
	v_rcp_f32_e32 v56, v56
	v_rcp_f32_e32 v57, v57
.LBB0_789:
	v_cvt_pk_bf16_f32 v54, v54, v55
	v_cvt_pk_bf16_f32 v55, v56, v57
	v_cvt_pk_bf16_f32 v56, v50, v51
	v_add_co_u32_e32 v50, vcc, 0x3cc000, v130
	v_cvt_pk_bf16_f32 v57, v52, v53
	s_nop 0
	v_addc_co_u32_e32 v51, vcc, 0, v131, vcc
	v_permlane16_swap_b32_e32 v54, v56
	v_permlane16_swap_b32_e32 v55, v57
	s_and_b64 vcc, exec, s[6:7]
	global_store_dwordx4 v[50:51], v[54:57], off
	s_cbranch_vccnz .LBB0_791
	v_pk_mul_f32 v[42:43], v[42:43], v[132:133]
	v_pk_mul_f32 v[44:45], v[44:45], v[132:133]
	v_pk_mul_f32 v[46:47], v[46:47], v[132:133]
	v_pk_mul_f32 v[48:49], v[48:49], v[132:133]
	v_exp_f32_e32 v42, v42
	v_exp_f32_e32 v43, v43
	v_exp_f32_e32 v44, v44
	v_exp_f32_e32 v45, v45
	v_exp_f32_e32 v46, v46
	v_exp_f32_e32 v47, v47
	v_exp_f32_e32 v48, v48
	v_exp_f32_e32 v49, v49
	v_pk_add_f32 v[42:43], v[42:43], 1.0 op_sel_hi:[1,0]
	v_pk_add_f32 v[44:45], v[44:45], 1.0 op_sel_hi:[1,0]
	v_pk_add_f32 v[46:47], v[46:47], 1.0 op_sel_hi:[1,0]
	v_pk_add_f32 v[48:49], v[48:49], 1.0 op_sel_hi:[1,0]
	v_rcp_f32_e32 v42, v42
	v_rcp_f32_e32 v43, v43
	v_rcp_f32_e32 v44, v44
	v_rcp_f32_e32 v45, v45
	v_rcp_f32_e32 v46, v46
	v_rcp_f32_e32 v47, v47
	v_rcp_f32_e32 v48, v48
	v_rcp_f32_e32 v49, v49
.LBB0_791:
	v_cvt_pk_bf16_f32 v46, v46, v47
	v_cvt_pk_bf16_f32 v47, v48, v49
	v_cvt_pk_bf16_f32 v48, v42, v43
	v_add_co_u32_e32 v42, vcc, 0x438000, v130
	v_cvt_pk_bf16_f32 v49, v44, v45
	s_nop 0
	v_addc_co_u32_e32 v43, vcc, 0, v131, vcc
	v_permlane16_swap_b32_e32 v46, v48
	v_permlane16_swap_b32_e32 v47, v49
	s_and_b64 vcc, exec, s[6:7]
	global_store_dwordx4 v[42:43], v[46:49], off
	s_cbranch_vccnz .LBB0_793
	v_pk_mul_f32 v[34:35], v[34:35], v[132:133]
	v_pk_mul_f32 v[36:37], v[36:37], v[132:133]
	v_pk_mul_f32 v[38:39], v[38:39], v[132:133]
	v_pk_mul_f32 v[40:41], v[40:41], v[132:133]
	v_exp_f32_e32 v34, v34
	v_exp_f32_e32 v35, v35
	v_exp_f32_e32 v36, v36
	v_exp_f32_e32 v37, v37
	v_exp_f32_e32 v38, v38
	v_exp_f32_e32 v39, v39
	v_exp_f32_e32 v40, v40
	v_exp_f32_e32 v41, v41
	v_pk_add_f32 v[34:35], v[34:35], 1.0 op_sel_hi:[1,0]
	v_pk_add_f32 v[36:37], v[36:37], 1.0 op_sel_hi:[1,0]
	v_pk_add_f32 v[38:39], v[38:39], 1.0 op_sel_hi:[1,0]
	v_pk_add_f32 v[40:41], v[40:41], 1.0 op_sel_hi:[1,0]
	v_rcp_f32_e32 v34, v34
	v_rcp_f32_e32 v35, v35
	v_rcp_f32_e32 v36, v36
	v_rcp_f32_e32 v37, v37
	v_rcp_f32_e32 v38, v38
	v_rcp_f32_e32 v39, v39
	v_rcp_f32_e32 v40, v40
	v_rcp_f32_e32 v41, v41
.LBB0_793:
	v_cvt_pk_bf16_f32 v38, v38, v39
	v_cvt_pk_bf16_f32 v39, v40, v41
	v_cvt_pk_bf16_f32 v40, v34, v35
	v_add_co_u32_e32 v34, vcc, 0x4a4000, v130
	v_cvt_pk_bf16_f32 v41, v36, v37
	s_nop 0
	v_addc_co_u32_e32 v35, vcc, 0, v131, vcc
	v_permlane16_swap_b32_e32 v38, v40
	v_permlane16_swap_b32_e32 v39, v41
	s_and_b64 vcc, exec, s[6:7]
	global_store_dwordx4 v[34:35], v[38:41], off
	s_cbranch_vccnz .LBB0_795
	v_pk_mul_f32 v[26:27], v[26:27], v[132:133]
	v_pk_mul_f32 v[28:29], v[28:29], v[132:133]
	v_pk_mul_f32 v[30:31], v[30:31], v[132:133]
	v_pk_mul_f32 v[32:33], v[32:33], v[132:133]
	v_exp_f32_e32 v26, v26
	v_exp_f32_e32 v27, v27
	v_exp_f32_e32 v28, v28
	v_exp_f32_e32 v29, v29
	v_exp_f32_e32 v30, v30
	v_exp_f32_e32 v31, v31
	v_exp_f32_e32 v32, v32
	v_exp_f32_e32 v33, v33
	v_pk_add_f32 v[26:27], v[26:27], 1.0 op_sel_hi:[1,0]
	v_pk_add_f32 v[28:29], v[28:29], 1.0 op_sel_hi:[1,0]
	v_pk_add_f32 v[30:31], v[30:31], 1.0 op_sel_hi:[1,0]
	v_pk_add_f32 v[32:33], v[32:33], 1.0 op_sel_hi:[1,0]
	v_rcp_f32_e32 v26, v26
	v_rcp_f32_e32 v27, v27
	v_rcp_f32_e32 v28, v28
	v_rcp_f32_e32 v29, v29
	v_rcp_f32_e32 v30, v30
	v_rcp_f32_e32 v31, v31
	v_rcp_f32_e32 v32, v32
	v_rcp_f32_e32 v33, v33
.LBB0_795:
	v_cvt_pk_bf16_f32 v30, v30, v31
	v_cvt_pk_bf16_f32 v31, v32, v33
	v_cvt_pk_bf16_f32 v32, v26, v27
	v_add_co_u32_e32 v26, vcc, 0x360000, v130
	v_cvt_pk_bf16_f32 v33, v28, v29
	s_nop 0
	v_addc_co_u32_e32 v27, vcc, 0, v131, vcc
	v_permlane16_swap_b32_e32 v30, v32
	v_permlane16_swap_b32_e32 v31, v33
	s_and_b64 vcc, exec, s[6:7]
	global_store_dwordx4 v[26:27], v[30:33], off offset:256
	s_cbranch_vccnz .LBB0_797
	v_pk_mul_f32 v[18:19], v[18:19], v[132:133]
	v_pk_mul_f32 v[20:21], v[20:21], v[132:133]
	v_pk_mul_f32 v[22:23], v[22:23], v[132:133]
	v_pk_mul_f32 v[24:25], v[24:25], v[132:133]
	v_exp_f32_e32 v18, v18
	v_exp_f32_e32 v19, v19
	v_exp_f32_e32 v20, v20
	v_exp_f32_e32 v21, v21
	v_exp_f32_e32 v22, v22
	v_exp_f32_e32 v23, v23
	v_exp_f32_e32 v24, v24
	v_exp_f32_e32 v25, v25
	v_pk_add_f32 v[18:19], v[18:19], 1.0 op_sel_hi:[1,0]
	v_pk_add_f32 v[20:21], v[20:21], 1.0 op_sel_hi:[1,0]
	v_pk_add_f32 v[22:23], v[22:23], 1.0 op_sel_hi:[1,0]
	v_pk_add_f32 v[24:25], v[24:25], 1.0 op_sel_hi:[1,0]
	v_rcp_f32_e32 v18, v18
	v_rcp_f32_e32 v19, v19
	v_rcp_f32_e32 v20, v20
	v_rcp_f32_e32 v21, v21
	v_rcp_f32_e32 v22, v22
	v_rcp_f32_e32 v23, v23
	v_rcp_f32_e32 v24, v24
	v_rcp_f32_e32 v25, v25
.LBB0_797:
	v_cvt_pk_bf16_f32 v22, v22, v23
	v_cvt_pk_bf16_f32 v23, v24, v25
	v_cvt_pk_bf16_f32 v24, v18, v19
	v_add_co_u32_e32 v18, vcc, 0x3cc000, v130
	v_cvt_pk_bf16_f32 v25, v20, v21
	s_nop 0
	v_addc_co_u32_e32 v19, vcc, 0, v131, vcc
	v_permlane16_swap_b32_e32 v22, v24
	v_permlane16_swap_b32_e32 v23, v25
	s_and_b64 vcc, exec, s[6:7]
	global_store_dwordx4 v[18:19], v[22:25], off offset:256
	s_cbranch_vccnz .LBB0_799
	v_pk_mul_f32 v[10:11], v[10:11], v[132:133]
	v_pk_mul_f32 v[12:13], v[12:13], v[132:133]
	v_pk_mul_f32 v[14:15], v[14:15], v[132:133]
	v_pk_mul_f32 v[16:17], v[16:17], v[132:133]
	v_exp_f32_e32 v10, v10
	v_exp_f32_e32 v11, v11
	v_exp_f32_e32 v12, v12
	v_exp_f32_e32 v13, v13
	v_exp_f32_e32 v14, v14
	v_exp_f32_e32 v15, v15
	v_exp_f32_e32 v16, v16
	v_exp_f32_e32 v17, v17
	v_pk_add_f32 v[10:11], v[10:11], 1.0 op_sel_hi:[1,0]
	v_pk_add_f32 v[12:13], v[12:13], 1.0 op_sel_hi:[1,0]
	v_pk_add_f32 v[14:15], v[14:15], 1.0 op_sel_hi:[1,0]
	v_pk_add_f32 v[16:17], v[16:17], 1.0 op_sel_hi:[1,0]
	v_rcp_f32_e32 v10, v10
	v_rcp_f32_e32 v11, v11
	v_rcp_f32_e32 v12, v12
	v_rcp_f32_e32 v13, v13
	v_rcp_f32_e32 v14, v14
	v_rcp_f32_e32 v15, v15
	v_rcp_f32_e32 v16, v16
	v_rcp_f32_e32 v17, v17
.LBB0_799:
	v_cvt_pk_bf16_f32 v14, v14, v15
	v_cvt_pk_bf16_f32 v15, v16, v17
	v_cvt_pk_bf16_f32 v16, v10, v11
	v_add_co_u32_e32 v10, vcc, 0x438000, v130
	v_cvt_pk_bf16_f32 v17, v12, v13
	s_nop 0
	v_addc_co_u32_e32 v11, vcc, 0, v131, vcc
	v_permlane16_swap_b32_e32 v14, v16
	v_permlane16_swap_b32_e32 v15, v17
	s_and_b64 vcc, exec, s[6:7]
	global_store_dwordx4 v[10:11], v[14:17], off offset:256
	s_cbranch_vccnz .LBB0_246
	v_pk_mul_f32 v[2:3], v[2:3], v[132:133]
	v_pk_mul_f32 v[4:5], v[4:5], v[132:133]
	v_pk_mul_f32 v[6:7], v[6:7], v[132:133]
	v_pk_mul_f32 v[8:9], v[8:9], v[132:133]
	v_exp_f32_e32 v2, v2
	v_exp_f32_e32 v3, v3
	v_exp_f32_e32 v4, v4
	v_exp_f32_e32 v5, v5
	v_exp_f32_e32 v6, v6
	v_exp_f32_e32 v7, v7
	v_exp_f32_e32 v8, v8
	v_exp_f32_e32 v9, v9
	v_pk_add_f32 v[2:3], v[2:3], 1.0 op_sel_hi:[1,0]
	v_pk_add_f32 v[4:5], v[4:5], 1.0 op_sel_hi:[1,0]
	v_pk_add_f32 v[6:7], v[6:7], 1.0 op_sel_hi:[1,0]
	v_pk_add_f32 v[8:9], v[8:9], 1.0 op_sel_hi:[1,0]
	v_rcp_f32_e32 v2, v2
	v_rcp_f32_e32 v3, v3
	v_rcp_f32_e32 v4, v4
	v_rcp_f32_e32 v5, v5
	v_rcp_f32_e32 v6, v6
	v_rcp_f32_e32 v7, v7
	v_rcp_f32_e32 v8, v8
	v_rcp_f32_e32 v9, v9
	s_branch .LBB0_246
